# even-mixer work queue: longest-first ticket order (5-chunk attention, conv, 4-chunk attention, context attention)
# speedup vs baseline: 1.0029x; 1.0029x over previous
.LBB0_1028:
	s_or_b64 exec, exec, s[0:1]
	s_add_i32 s0, 0, 0x23e80
	s_cmp_lg_u32 s0, -1
	s_cselect_b32 s0, s0, 0
	s_cselect_b32 s1, s55, 0
	v_mov_b32_e32 v2, s0
	v_mov_b32_e32 v3, s1
	s_waitcnt lgkmcnt(0)
	s_barrier
	ds_read_b32 v2, v2
	s_waitcnt vmcnt(0) lgkmcnt(0)
	v_readfirstlane_b32 s84, v2
	s_cmp_ge_u32 s84, 0x330
	s_cbranch_scc1 .Lmixq_keep
	s_cmp_lt_u32 s84, 480
	s_cbranch_scc1 .Lmixq_a
	s_cmp_lt_u32 s84, 752
	s_cbranch_scc1 .Lmixq_b
	s_cmp_lt_u32 s84, 784
	s_cbranch_scc1 .Lmixq_c
	s_sub_u32 s84, s84, 272
	s_branch .Lmixq_done
.Lmixq_a:
	s_mul_hi_u32 s85, s84, 0x88888889
	s_lshr_b32 s85, s85, 6
	s_mul_i32 s86, s85, 120
	s_sub_u32 s86, s84, s86
	s_lshl_b32 s85, s85, 7
	s_add_u32 s84, s85, s86
	s_add_u32 s84, s84, 4
	s_branch .Lmixq_done
.Lmixq_b:
	s_add_u32 s84, s84, 64
	s_branch .Lmixq_done
.Lmixq_c:
	s_sub_u32 s86, s84, 752
	s_lshr_b32 s85, s86, 3
	s_lshl_b32 s85, s85, 7
	s_and_b32 s87, s86, 3
	s_bitcmp1_b32 s86, 2
	s_cselect_b32 s86, 124, 0
	s_add_u32 s84, s85, s86
	s_add_u32 s84, s84, s87
.Lmixq_done:
	v_mov_b32_e32 v2, s84
.Lmixq_keep:
	s_movk_i32 s0, 0x330
	s_waitcnt lgkmcnt(0)
	v_cmp_gt_i32_e32 vcc, s0, v2
	s_mov_b64 s[0:1], -1
	s_and_saveexec_b64 s[12:13], vcc
	s_cbranch_execz .LBB0_1023
	s_movk_i32 s0, 0x21f
	v_cmp_lt_i32_e32 vcc, s0, v2
	s_and_saveexec_b64 s[0:1], vcc
	s_xor_b64 s[4:5], exec, s[0:1]
	s_cbranch_execz .LBB0_1167
	s_movk_i32 s0, 0x31f
	v_cmp_lt_u32_e32 vcc, s0, v2
	v_lshlrev_b32_e32 v2, 6, v2
	s_and_saveexec_b64 s[0:1], vcc
	s_xor_b64 s[0:1], exec, s[0:1]
	v_add_u32_e32 v1, 0x7fff3800, v2
	v_and_b32_e32 v1, 0x7fffff00, v1
	v_add_u32_e32 v1, 0x4000, v1
	v_and_b32_e32 v136, 0xc0, v2
	s_or_saveexec_b64 s[0:1], s[0:1]
	v_mov_b32_e32 v138, 0x100
	s_xor_b64 exec, exec, s[0:1]
	v_add_u32_e32 v2, 0xffff7800, v2
	v_and_b32_e32 v1, 0x7ffff000, v2
	v_and_b32_e32 v136, 0xfc0, v2
	v_mov_b32_e32 v138, 0x1000
	s_or_b64 exec, exec, s[0:1]
	s_cmp_lg_u32 s57, -1
	s_cselect_b32 s0, s57, 0
	s_cselect_b32 s1, s55, 0
	s_cmp_lg_u32 s58, -1
	v_mov_b32_e32 v137, v224
	v_mov_b32_e32 v2, s0
	v_mov_b32_e32 v3, s1
	s_cselect_b32 s0, s58, 0
	ds_read_b32 v68, v2
	s_waitcnt vmcnt(0) lgkmcnt(0)
	s_cselect_b32 s1, s55, 0
	v_mov_b32_e32 v2, s0
	s_add_i32 s0, 0, 0x23f70
	s_cmp_lg_u32 s0, -1
	v_mov_b32_e32 v3, s1
	s_cselect_b32 s0, s0, 0
	ds_read_b32 v69, v2
	s_waitcnt vmcnt(0) lgkmcnt(0)
	s_cselect_b32 s1, s55, 0
	v_mov_b32_e32 v2, s0
	s_add_i32 s0, 0, 0x23f74
	s_cmp_lg_u32 s0, -1
	v_mov_b32_e32 v3, s1
	s_cselect_b32 s0, s0, 0
	s_cselect_b32 s1, s55, 0
	ds_read_b32 v4, v2
	s_waitcnt vmcnt(0) lgkmcnt(0)
	v_mov_b32_e32 v2, s0
	v_mov_b32_e32 v3, s1
	ds_read_b32 v5, v2
	s_waitcnt vmcnt(0) lgkmcnt(0)
	v_lshlrev_b32_e32 v2, 1, v137
	v_and_b32_e32 v70, 0x1fe, v2
	v_mov_b32_e32 v3, v0
	v_lshlrev_b32_e32 v2, 2, v70
	s_movk_i32 s6, 0x1000
	v_ashrrev_i32_e32 v71, 8, v137
	v_lshl_add_u32 v139, v71, 16, 0
	s_mov_b32 s43, 0
	v_add_u32_e32 v140, v139, v2
	s_mov_b64 s[16:17], 0
	s_mov_b64 s[14:15], -1
	v_mov_b32_e32 v72, 0
	v_mov_b32_e32 v73, 0
	s_waitcnt lgkmcnt(0)
	v_readfirstlane_b32 s7, v69
	v_mov_b32_e32 v69, v0
	v_readfirstlane_b32 s0, v4
	v_readfirstlane_b32 s1, v5
	s_nop 1
	v_lshl_add_u64 v[58:59], s[0:1], 0, v[2:3]
	v_add_co_u32_e32 v28, vcc, s6, v58
	s_movk_i32 s6, 0x2000
	s_nop 0
	v_addc_co_u32_e32 v29, vcc, 0, v59, vcc
	v_add_co_u32_e32 v12, vcc, s6, v58
	s_movk_i32 s6, 0x3000
	s_nop 0
	v_addc_co_u32_e32 v13, vcc, 0, v59, vcc
	v_add_co_u32_e32 v30, vcc, s6, v58
	s_movk_i32 s6, 0x4000
	s_nop 0
	v_addc_co_u32_e32 v31, vcc, 0, v59, vcc
	v_add_co_u32_e32 v18, vcc, s6, v58
	s_movk_i32 s6, 0x5000
	s_nop 0
	v_addc_co_u32_e32 v19, vcc, 0, v59, vcc
	v_add_co_u32_e32 v32, vcc, s6, v58
	s_movk_i32 s6, 0x6000
	s_nop 0
	v_addc_co_u32_e32 v33, vcc, 0, v59, vcc
	v_add_co_u32_e32 v24, vcc, s6, v58
	s_movk_i32 s6, 0x7000
	s_nop 0
	v_addc_co_u32_e32 v25, vcc, 0, v59, vcc
	v_add_co_u32_e32 v34, vcc, s6, v58
	s_mov_b32 s6, 0x8000
	s_nop 0
	v_addc_co_u32_e32 v35, vcc, 0, v59, vcc
	v_add_co_u32_e32 v38, vcc, s6, v58
	s_mov_b32 s6, 0x9000
	s_nop 0
	v_addc_co_u32_e32 v39, vcc, 0, v59, vcc
	v_add_co_u32_e32 v60, vcc, s6, v58
	s_mov_b32 s6, 0xa000
	s_nop 0
	v_addc_co_u32_e32 v61, vcc, 0, v59, vcc
	v_add_co_u32_e32 v44, vcc, s6, v58
	v_readfirstlane_b32 s6, v68
	s_nop 0
	v_addc_co_u32_e32 v45, vcc, 0, v59, vcc
	global_load_dwordx2 v[4:5], v2, s[0:1]
	global_load_dwordx2 v[6:7], v2, s[0:1] offset:2048
	global_load_dwordx2 v[8:9], v[12:13], off offset:-4096
	global_load_dwordx2 v[10:11], v[12:13], off
	s_nop 0
	global_load_dwordx2 v[12:13], v[12:13], off offset:2048
	s_nop 0
	global_load_dwordx2 v[14:15], v[18:19], off offset:-4096
	global_load_dwordx2 v[16:17], v[18:19], off
	s_nop 0
	global_load_dwordx2 v[18:19], v[18:19], off offset:2048
	s_nop 0
	global_load_dwordx2 v[20:21], v[24:25], off offset:-4096
	global_load_dwordx2 v[22:23], v[24:25], off
	s_nop 0
	global_load_dwordx2 v[24:25], v[24:25], off offset:2048
	s_nop 0
	global_load_dwordx2 v[26:27], v[38:39], off offset:-4096
	s_nop 0
	global_load_dwordx2 v[28:29], v[28:29], off offset:2048
	s_nop 0
	global_load_dwordx2 v[30:31], v[30:31], off offset:2048
	s_nop 0
	global_load_dwordx2 v[32:33], v[32:33], off offset:2048
	s_nop 0
	global_load_dwordx2 v[34:35], v[34:35], off offset:2048
	s_nop 0
	global_load_dwordx2 v[36:37], v[38:39], off
	s_nop 0
	global_load_dwordx2 v[38:39], v[38:39], off offset:2048
	s_nop 0
	global_load_dwordx2 v[40:41], v[44:45], off offset:-4096
	global_load_dwordx2 v[42:43], v[44:45], off
	s_mov_b32 s0, 0xb000
	v_add_co_u32_e32 v62, vcc, s0, v58
	s_mov_b32 s0, 0xc000
	s_nop 0
	v_addc_co_u32_e32 v63, vcc, 0, v59, vcc
	v_add_co_u32_e32 v50, vcc, s0, v58
	s_mov_b32 s0, 0xd000
	s_nop 0
	v_addc_co_u32_e32 v51, vcc, 0, v59, vcc
	v_add_co_u32_e32 v64, vcc, s0, v58
	s_mov_b32 s0, 0xe000
	s_nop 0
	v_addc_co_u32_e32 v65, vcc, 0, v59, vcc
	v_add_co_u32_e32 v56, vcc, s0, v58
	s_mov_b32 s0, 0xf000
	s_nop 0
	v_addc_co_u32_e32 v57, vcc, 0, v59, vcc
	v_add_co_u32_e32 v66, vcc, s0, v58
	s_add_i32 s0, 0, 0x23f78
	s_cmp_lg_u32 s0, -1
	s_cselect_b32 s0, s0, 0
	global_load_dwordx2 v[44:45], v[44:45], off offset:2048
	s_nop 0
	global_load_dwordx2 v[46:47], v[50:51], off offset:-4096
	global_load_dwordx2 v[48:49], v[50:51], off
	s_nop 0
	global_load_dwordx2 v[50:51], v[50:51], off offset:2048
	s_nop 0
	global_load_dwordx2 v[52:53], v[56:57], off offset:-4096
	global_load_dwordx2 v[54:55], v[56:57], off
	s_nop 0
	global_load_dwordx2 v[56:57], v[56:57], off offset:2048
	v_addc_co_u32_e32 v67, vcc, 0, v59, vcc
	global_load_dwordx2 v[58:59], v[60:61], off offset:2048
	s_nop 0
	global_load_dwordx2 v[60:61], v[62:63], off offset:2048
	s_nop 0
	global_load_dwordx2 v[62:63], v[64:65], off offset:2048
	s_nop 0
	global_load_dwordx2 v[64:65], v[66:67], off
	s_cselect_b32 s1, s55, 0
	v_mov_b32_e32 v66, s0
	s_add_i32 s0, 0, 0x23f7c
	s_cmp_lg_u32 s0, -1
	v_mov_b32_e32 v67, s1
	s_cselect_b32 s0, s0, 0
	s_cselect_b32 s1, s55, 0
	ds_read_b32 v3, v66
	s_waitcnt vmcnt(0) lgkmcnt(0)
	v_mov_b32_e32 v66, s0
	v_mov_b32_e32 v67, s1
	ds_read_b32 v66, v66
	s_waitcnt vmcnt(0) lgkmcnt(0)
	v_lshlrev_b32_e32 v68, 1, v70
	v_lshl_add_u64 v[68:69], s[6:7], 0, v[68:69]
	v_mov_b32_e32 v70, 0
	v_lshl_add_u64 v[68:69], v[68:69], 0, s[80:81]
	v_mov_b32_e32 v74, v70
	v_mov_b32_e32 v75, v70
	v_mov_b32_e32 v76, v70
	v_mov_b32_e32 v77, v70
	v_mov_b32_e32 v78, v70
	v_mov_b32_e32 v79, v70
	v_mov_b32_e32 v80, v70
	v_mov_b32_e32 v81, v70
	v_mov_b32_e32 v82, v70
	v_mov_b32_e32 v83, v70
	v_mov_b32_e32 v84, v70
	v_mov_b32_e32 v85, v70
	v_mov_b32_e32 v86, v70
	v_mov_b32_e32 v87, v70
	v_mov_b32_e32 v88, v70
	v_mov_b32_e32 v89, v70
	v_mov_b32_e32 v90, v70
	v_mov_b32_e32 v91, v70
	v_mov_b32_e32 v92, v70
	v_mov_b32_e32 v93, v70
	v_mov_b32_e32 v94, v70
	v_mov_b32_e32 v95, v70
	v_mov_b32_e32 v96, v70
	v_mov_b32_e32 v97, v70
	v_mov_b32_e32 v98, v70
	v_mov_b32_e32 v99, v70
	v_mov_b32_e32 v100, v70
	v_mov_b32_e32 v101, v70
	v_mov_b32_e32 v102, v70
	v_mov_b32_e32 v103, v70
	v_mov_b32_e32 v104, v70
	v_mov_b32_e32 v105, v70
	v_mov_b32_e32 v106, v70
	v_mov_b32_e32 v107, v70
	v_mov_b32_e32 v108, v70
	v_mov_b32_e32 v109, v70
	v_mov_b32_e32 v110, v70
	v_mov_b32_e32 v111, v70
	v_mov_b32_e32 v112, v70
	v_mov_b32_e32 v113, v70
	v_mov_b32_e32 v114, v70
	v_mov_b32_e32 v115, v70
	v_mov_b32_e32 v116, v70
	v_mov_b32_e32 v117, v70
	v_mov_b32_e32 v118, v70
	v_mov_b32_e32 v119, v70
	v_mov_b32_e32 v120, v70
	v_mov_b32_e32 v121, v70
	v_mov_b32_e32 v122, v70
	v_mov_b32_e32 v123, v70
	v_mov_b32_e32 v124, v70
	v_mov_b32_e32 v125, v70
	v_mov_b32_e32 v126, v70
	v_mov_b32_e32 v127, v70
	v_mov_b32_e32 v128, v70
	v_mov_b32_e32 v129, v70
	v_mov_b32_e32 v134, v70
	v_mov_b32_e32 v135, v70
	s_waitcnt lgkmcnt(0)
	v_readfirstlane_b32 s0, v3
	v_lshlrev_b32_e32 v3, 5, v71
	v_add3_u32 v3, v136, v3, -15
	v_readfirstlane_b32 s1, v66
	v_mov_b32_e32 v71, v70
	s_nop 3
	global_load_dwordx2 v[66:67], v2, s[0:1]
	s_branch .LBB0_1036
